# LN row-stat exchange: tagged 8-byte slots polled directly (no counter atomic, no acquire/barrier round trip); P0 initialises slot tags
# speedup vs baseline: 1.0084x; 1.0020x over previous
.LBB0_56:
	s_lshl_b32 s20, s79, 9
	v_writelane_b32 v253, s52, 49
	v_add_u32_e32 v2, s20, v1
	v_readlane_b32 s0, v253, 4
	v_readlane_b32 s1, v253, 5
	v_lshlrev_b32_e32 v4, 3, v2
	v_mov_b32_e32 v5, 0
	v_add_u32_e32 v4, 0x200000, v4
	v_mov_b32_e32 v6, 0
	v_bfrev_b32_e32 v7, 1
	v_lshl_add_u64 v[4:5], s[0:1], 0, v[4:5]
	global_store_dwordx2 v[4:5], v[6:7], off
	s_mov_b32 s0, 0x10000
	v_writelane_b32 v253, s53, 50
	v_cmp_gt_i32_e32 vcc, s0, v2
	s_and_saveexec_b64 s[2:3], vcc
	s_cbranch_execz .LBB0_64
	v_readlane_b32 s4, v253, 2
	s_lshl_b32 s4, s4, 9
	v_readlane_b32 s5, v253, 3
	v_cvt_f32_u32_e32 v4, s4
	v_add_u32_e32 v3, s4, v2
	v_mov_b32_e32 v5, s4
	v_cmp_gt_i32_e32 vcc, s0, v3
	v_rcp_iflag_f32_e32 v4, v4
	s_sub_i32 s5, 0, s4
	v_max_i32_e32 v6, 0x10000, v3
	v_addc_co_u32_e64 v5, s[0:1], v2, v5, vcc
	v_mul_f32_e32 v4, 0x4f7ffffe, v4
	v_cvt_u32_f32_e32 v4, v4
	v_sub_u32_e32 v5, v6, v5
	s_mov_b64 s[6:7], -1
	v_mul_lo_u32 v6, s5, v4
	v_mul_hi_u32 v6, v4, v6
	v_add_u32_e32 v4, v4, v6
	v_mul_hi_u32 v4, v5, v4
	v_mul_lo_u32 v6, v4, s4
	v_sub_u32_e32 v5, v5, v6
	v_add_u32_e32 v7, 1, v4
	v_cmp_le_u32_e64 s[0:1], s4, v5
	v_subrev_u32_e32 v6, s4, v5
	s_nop 0
	v_cndmask_b32_e64 v4, v4, v7, s[0:1]
	v_cndmask_b32_e64 v5, v5, v6, s[0:1]
	v_add_u32_e32 v6, 1, v4
	v_cmp_le_u32_e64 s[0:1], s4, v5
	s_nop 1
	v_cndmask_b32_e64 v4, v4, v6, s[0:1]
	v_addc_co_u32_e32 v6, vcc, 1, v4, vcc
	v_cmp_lt_u32_e32 vcc, 1, v6
	v_mov_b32_e32 v4, v2
	s_and_saveexec_b64 s[0:1], vcc
	s_cbranch_execz .LBB0_61
	v_readlane_b32 s6, v253, 2
	v_and_b32_e32 v7, -2, v6
	v_readlane_b32 s7, v253, 3
	s_lshl_b32 s5, s6, 10
	v_readlane_b32 s10, v253, 13
	s_mov_b32 s8, s5
	s_mov_b64 s[6:7], 0
	v_mov_b32_e32 v8, 0
	v_mov_b32_e32 v9, v7
	v_mov_b64_e32 v[4:5], v[2:3]
	v_readlane_b32 s11, v253, 14

.LBB0_709:
	s_or_b64 exec, exec, s[12:13]
	s_waitcnt lgkmcnt(0)
	s_barrier
	v_add_u32_e32 v128, s54, v207
	v_ashrrev_i32_e32 v129, 31, v128
	s_and_saveexec_b64 s[12:13], s[6:7]
	s_cbranch_execz .LBB0_711
	s_waitcnt lgkmcnt(0)
	ds_read_b128 v[130:133], v232
	ds_read_b128 v[134:137], v232 offset:16
	v_readlane_b32 s52, v253, 62
	v_readlane_b32 s53, v253, 63
	s_ashr_i32 s51, s50, 31
	s_waitcnt lgkmcnt(1)
	v_add_f32_e32 v138, v130, v132
	s_waitcnt lgkmcnt(0)
	v_add_f32_e32 v138, v138, v134
	v_add_f32_e32 v139, v138, v136
	v_fmamk_f32 v130, v139, 0xbe800000, v130
	v_fmac_f32_e32 v132, 0xbe800000, v139
	v_fmamk_f32 v134, v139, 0xbe800000, v134
	v_fmac_f32_e32 v136, 0xbe800000, v139
	v_mul_f32_e32 v141, v130, v130
	v_mul_f32_e32 v143, v132, v132
	v_mul_f32_e32 v145, v134, v134
	v_mul_f32_e32 v147, v136, v136
	v_mov_b32_e32 v140, v131
	v_mov_b32_e32 v142, v133
	v_mov_b32_e32 v144, v135
	v_mov_b32_e32 v146, v137
	v_pk_add_f32 v[130:131], v[140:141], v[142:143]
	v_pk_add_f32 v[132:133], v[144:145], v[146:147]
	v_mul_f32_e32 v138, 0x3e800000, v139
	v_pk_add_f32 v[130:131], v[130:131], v[132:133]
	v_lshlrev_b64 v[132:133], 5, v[128:129]
	v_fmac_f32_e32 v130, 0x42800000, v131
	v_lshl_add_u64 v[132:133], s[52:53], 0, v[132:133]
	v_lshl_add_u64 v[132:133], s[50:51], 3, v[132:133]
	v_mov_b32_e32 v139, v130
	v_readlane_b32 vcc_lo, v253, 4
	s_sub_u32 vcc_lo, s67, vcc_lo
	s_lshl_b32 vcc_lo, vcc_lo, 16
	s_and_b32 vcc_lo, vcc_lo, 0x80000000
	v_or_b32_e32 v139, vcc_lo, v139
	global_store_dwordx2 v[132:133], v[138:139], off sc1
.LBB0_711:
	s_or_b64 exec, exec, s[12:13]
	v_lshlrev_b64 v[160:161], 2, v[186:187]
	v_lshl_add_u64 v[162:163], s[30:31], 0, v[160:161]
	v_lshl_add_u64 v[160:161], s[34:35], 0, v[160:161]
	global_load_dwordx4 v[144:147], v[162:163], off offset:16
	global_load_dwordx4 v[152:155], v[162:163], off
	global_load_dwordx4 v[148:151], v[160:161], off offset:16
	global_load_dwordx4 v[156:159], v[160:161], off
	s_and_saveexec_b64 s[50:51], s[6:7]
	s_cbranch_execz .LBB0_722
	v_readlane_b32 s12, v253, 62
	v_lshlrev_b64 v[128:129], 5, v[128:129]
	v_readlane_b32 s13, v253, 63
	s_nop 1
	v_lshl_add_u64 v[128:129], s[12:13], 0, v[128:129]
	v_readlane_b32 s12, v253, 4
	s_sub_u32 s12, s67, s12
	s_lshl_b32 s12, s12, 16
	s_and_b32 s12, s12, 0x80000000
	s_mov_b32 s13, 0x100000
.Lln_poll:
	global_load_dwordx2 v[130:131], v[128:129], off sc1
	global_load_dwordx2 v[132:133], v[128:129], off offset:8 sc1
	global_load_dwordx2 v[140:141], v[128:129], off offset:16 sc1
	global_load_dwordx2 v[142:143], v[128:129], off offset:24 sc1
	s_waitcnt vmcnt(0)
	v_xor_b32_e32 v134, s12, v131
	v_xor_b32_e32 v135, s12, v133
	v_xor_b32_e32 v136, s12, v141
	v_xor_b32_e32 v137, s12, v143
	v_or_b32_e32 v134, v134, v135
	v_or3_b32 v134, v134, v136, v137
	v_cmp_gt_i32_e32 vcc, 0, v134
	s_and_b64 vcc, exec, vcc
	s_cbranch_vccz .Lln_ok
	s_sub_u32 s13, s13, 1
	s_cmp_eq_u32 s13, 0
	s_cbranch_scc1 .Lln_ok
	s_sleep 1
	s_branch .Lln_poll
.Lln_ok:
	v_and_b32_e32 v131, 0x7fffffff, v131
	v_and_b32_e32 v133, 0x7fffffff, v133
	v_and_b32_e32 v141, 0x7fffffff, v141
	v_and_b32_e32 v143, 0x7fffffff, v143
	s_mov_b32 s12, 0xf800000
	v_add_f32_e32 v134, 0, v130
	v_add_f32_e32 v136, v134, v132
	v_mov_b32_e32 v134, v140
	v_mov_b32_e32 v135, v141
	v_add_f32_e32 v136, v136, v134
	v_mov_b32_e32 v128, v142
	v_mov_b32_e32 v129, v143
	v_add_f32_e32 v137, v136, v128
	v_fmamk_f32 v130, v137, 0xbe800000, v130
	v_mul_f32_e32 v138, 0x43800000, v130
	v_fmac_f32_e32 v131, v130, v138
	v_add_f32_e32 v130, 0, v131
	v_fmamk_f32 v131, v137, 0xbe800000, v132
	v_mul_f32_e32 v132, 0x43800000, v131
	v_fmac_f32_e32 v133, v131, v132
	v_fmamk_f32 v131, v137, 0xbe800000, v134
	v_mul_f32_e32 v132, 0x43800000, v131
	v_fmamk_f32 v128, v137, 0xbe800000, v128
	v_add_f32_e32 v130, v133, v130
	v_fmac_f32_e32 v135, v131, v132
	v_mul_f32_e32 v131, 0x43800000, v128
	v_add_f32_e32 v130, v135, v130
	v_fmac_f32_e32 v129, v128, v131
	v_add_f32_e32 v128, v129, v130
	v_mov_b32_e32 v129, 0x3727c5ac
	v_fmamk_f32 v128, v128, 0x3a800000, v129
	v_cmp_gt_f32_e32 vcc, s12, v128
	v_mul_f32_e32 v129, 0x4f800000, v128
	v_mul_f32_e32 v136, 0x3e800000, v137
	v_cndmask_b32_e32 v128, v128, v129, vcc
	v_sqrt_f32_e32 v129, v128
	s_nop 0
	v_add_u32_e32 v130, -1, v129
	v_fma_f32 v131, -v130, v129, v128
	v_cmp_ge_f32_e64 s[12:13], 0, v131
	v_add_u32_e32 v131, 1, v129
	s_nop 0
	v_cndmask_b32_e64 v130, v129, v130, s[12:13]
	v_fma_f32 v129, -v131, v129, v128
	v_cmp_lt_f32_e64 s[12:13], 0, v129
	s_nop 1
	v_cndmask_b32_e64 v129, v130, v131, s[12:13]
	v_mul_f32_e32 v130, 0x37800000, v129
	v_cndmask_b32_e32 v129, v129, v130, vcc
	v_mov_b32_e32 v130, 0x260
	v_cmp_class_f32_e32 vcc, v128, v130
	s_nop 1
	v_cndmask_b32_e32 v128, v129, v128, vcc
	v_div_scale_f32 v129, s[12:13], v128, v128, 1.0
	v_rcp_f32_e32 v130, v129
	s_nop 0
	v_fma_f32 v131, -v129, v130, 1.0
	v_fmac_f32_e32 v130, v131, v130
	v_div_scale_f32 v131, vcc, 1.0, v128, 1.0
	v_mul_f32_e32 v132, v131, v130
	v_fma_f32 v133, -v129, v132, v131
	v_fmac_f32_e32 v132, v133, v130
	v_fma_f32 v129, -v129, v132, v131
	v_div_fmas_f32 v129, v129, v130, v132
	v_div_fixup_f32 v137, v129, v128, 1.0
	ds_write_b64 v208, v[136:137]
